# adds the trimmed staging y-pass (lane addresses formed once, shared store address) and the attention row-max / PV prefetch edits to the placement-compensated combination
# speedup vs baseline: 1.0088x; 1.0088x over previous
.LBB0_1049:
	s_and_b64 vcc, exec, s[0:1]
	s_cbranch_vccz .LBB0_1102
	s_ashr_i32 s0, s2, 5
	s_bfe_u32 s7, s2, 0x30002
	v_lshlrev_b32_e32 v2, 2, v169
	s_ashr_i32 s1, s0, 31
	s_mul_i32 s10, s0, 0x1c8e400
	v_lshl_or_b32 v28, s7, 6, v2
	v_mov_b32_e32 v29, 0
	s_mul_hi_i32 s11, s0, 0x1c8e400
	s_add_u32 s10, s38, s10
	v_lshlrev_b64 v[6:7], 2, v[28:29]
	s_addc_u32 s11, s39, s11
	v_lshlrev_b32_e32 v28, 1, v28
	v_lshl_add_u64 v[30:31], s[10:11], 0, v[28:29]
	s_mul_i32 s11, s0, 0x804000
	s_mul_hi_i32 s10, s0, 0x804000
	s_add_u32 s4, s4, s11
	s_addc_u32 s5, s5, s10
	v_lshl_add_u64 v[32:33], s[4:5], 0, v[28:29]
	s_add_u32 s4, s16, s11
	s_addc_u32 s5, s17, s10
	v_lshl_add_u64 v[34:35], s[4:5], 0, v[28:29]
	s_mul_i32 s5, s0, 0x40200
	s_mul_hi_i32 s4, s0, 0x40200
	s_add_u32 s5, s28, s5
	s_addc_u32 s4, s29, s4
	s_lshl_b32 s10, s7, 2
	s_add_u32 s5, s5, s10
	s_addc_u32 s4, s4, 0
	s_add_u32 s36, s5, 0xfd30000
	s_addc_u32 s37, s4, 0
	s_lshl_b64 s[0:1], s[0:1], 23
	s_add_u32 s0, s44, s0
	s_addc_u32 s1, s45, s1
	s_lshl_b32 s4, s7, 7
	s_add_u32 s0, s0, s4
	s_addc_u32 s1, s1, 0
	s_lshl_b32 s4, s6, 5
	s_add_u32 s0, s0, s4
	s_addc_u32 s1, s1, 0
	s_add_u32 s40, s28, 0xfdf3f00
	v_readlane_b32 s4, v255, 5
	s_addc_u32 s41, s29, 0
	s_lshl_b32 s35, s4, 2
	v_lshlrev_b32_e32 v28, 3, v166
	s_add_i32 s62, s35, -16
	v_lshl_add_u64 v[26:27], s[0:1], 0, v[28:29]
	v_or_b32_e32 v28, s62, v166
	s_movk_i32 s63, 0xe40
	v_mad_u64_u32 v[2:3], s[0:1], v28, s63, v[30:31]
	v_max_i32_e32 v4, 1, v28
	global_load_dwordx2 v[24:25], v[2:3], off
	global_load_dwordx2 v[50:51], v[2:3], off offset:1024
	global_load_dwordx2 v[52:53], v[2:3], off offset:2048
	v_add_u32_e32 v2, -1, v4
	v_mad_u64_u32 v[2:3], s[0:1], v2, s63, v[30:31]
	v_readlane_b32 s64, v255, 7
	global_load_dwordx2 v[54:55], v[2:3], off
	global_load_dwordx2 v[56:57], v[2:3], off offset:1024
	global_load_dwordx2 v[58:59], v[2:3], off offset:2048
	v_lshlrev_b64 v[2:3], 10, v[28:29]
	v_readlane_b32 s78, v255, 21
	v_readlane_b32 s79, v255, 22
	v_lshl_add_u64 v[4:5], v[32:33], 0, v[2:3]
	v_lshl_add_u64 v[2:3], v[34:35], 0, v[2:3]
	v_lshl_add_u64 v[18:19], s[78:79], 0, v[6:7]
	global_load_dwordx2 v[60:61], v[4:5], off
	global_load_dwordx2 v[62:63], v[2:3], off
	v_lshl_add_u64 v[10:11], s[46:47], 0, v[6:7]
	global_load_dwordx4 v[2:5], v[18:19], off
	v_lshl_add_u64 v[14:15], s[48:49], 0, v[6:7]
	global_load_dwordx4 v[6:9], v[18:19], off offset:2048
	v_add_co_u32_e32 v18, vcc, 0x1000, v18
	global_load_dwordx4 v[10:13], v[10:11], off
	s_nop 0
	global_load_dwordx4 v[14:17], v[14:15], off
	v_addc_co_u32_e32 v19, vcc, 0, v19, vcc
	global_load_dwordx4 v[18:21], v[18:19], off
	v_or_b32_e32 v36, s35, v166
	v_add_u32_e32 v23, -1, v36
	v_cmp_eq_u32_e32 vcc, 0, v28
	v_mov_b32_e32 v37, v29
	v_mad_u64_u32 v[42:43], s[0:1], v36, s63, v[30:31]
	v_mad_u64_u32 v[46:47], s[0:1], v23, s63, v[30:31]
	v_cndmask_b32_e64 v72, 1.0, 0, vcc
	v_lshlrev_b64 v[38:39], 10, v[36:37]
	v_lshlrev_b64 v[40:41], 5, v[28:29]
	s_add_i32 s0, s35, 16
	v_lshlrev_b64 v[36:37], 5, v[36:37]
	v_lshl_add_u64 v[48:49], v[32:33], 0, v[38:39]
	v_lshl_add_u64 v[64:65], v[34:35], 0, v[38:39]
	v_lshl_add_u64 v[38:39], s[36:37], 0, v[40:41]
	v_lshl_add_u64 v[66:67], s[36:37], 0, v[36:37]
	global_load_dwordx2 v[36:37], v[46:47], off
	global_load_dwordx2 v[44:45], v[46:47], off offset:1024
	s_nop 0
	global_load_dwordx2 v[46:47], v[46:47], off offset:2048
	s_nop 0
	global_load_dwordx2 v[48:49], v[48:49], off
	s_nop 0
	global_load_dword v86, v[38:39], off
	s_nop 0
	global_load_dwordx2 v[38:39], v[42:43], off
	global_load_dwordx2 v[40:41], v[42:43], off offset:1024
	s_nop 0
	global_load_dwordx2 v[42:43], v[42:43], off offset:2048
	s_cmp_eq_u32 s4, 4
	v_readlane_b32 s69, v255, 12
	s_cselect_b64 s[46:47], -1, 0
	v_readlane_b32 s70, v255, 13
	s_movk_i32 s6, 0x90
	s_add_i32 s69, s35, -15
	v_readlane_b32 s71, v255, 14
	s_add_i32 s70, s35, -14
	s_add_i32 s71, s35, -13
	v_readlane_b32 s65, v255, 8
	v_readlane_b32 s66, v255, 9
	v_readlane_b32 s67, v255, 10
	v_readlane_b32 s68, v255, 11
	v_readlane_b32 s72, v255, 15
	s_mov_b32 s57, 0
	v_cmp_eq_u32_e64 s[4:5], 0, v178
	s_sub_i32 s67, s3, 64
	s_lshl_b32 s68, s62, 7
	s_lshl_b32 s66, s69, 7
	s_lshl_b32 s65, s70, 7
	s_lshl_b32 s64, s71, 7
	s_mov_b32 s72, 0
	v_readlane_b32 s73, v255, 16
	v_readlane_b32 s74, v255, 17
	v_readlane_b32 s75, v255, 18
	v_readlane_b32 s76, v255, 19
	v_readlane_b32 s77, v255, 20
	s_waitcnt vmcnt(20)
	v_lshlrev_b32_e32 v68, 16, v24
	v_and_b32_e32 v69, 0xffff0000, v24
	s_waitcnt vmcnt(19)
	v_lshlrev_b32_e32 v74, 16, v50
	v_and_b32_e32 v75, 0xffff0000, v50
	v_lshlrev_b32_e32 v76, 16, v51
	v_and_b32_e32 v77, 0xffff0000, v51
	s_waitcnt vmcnt(18)
	v_lshlrev_b32_e32 v78, 16, v52
	v_and_b32_e32 v79, 0xffff0000, v52
	v_lshlrev_b32_e32 v80, 16, v53
	v_and_b32_e32 v81, 0xffff0000, v53
	s_waitcnt vmcnt(17)
	v_lshlrev_b32_e32 v50, 16, v54
	v_and_b32_e32 v51, 0xffff0000, v54
	v_lshlrev_b32_e32 v52, 16, v55
	v_and_b32_e32 v53, 0xffff0000, v55
	s_waitcnt vmcnt(16)
	v_lshlrev_b32_e32 v82, 16, v56
	v_and_b32_e32 v83, 0xffff0000, v56
	v_lshlrev_b32_e32 v54, 16, v57
	v_and_b32_e32 v55, 0xffff0000, v57
	v_xor_b32_e32 v57, 0x80000000, v69
	v_xor_b32_e32 v56, 0x80000000, v68
	v_lshlrev_b32_e32 v24, 16, v25
	v_and_b32_e32 v25, 0xffff0000, v25
	v_pk_fma_f32 v[50:51], v[72:73], v[50:51], v[56:57] op_sel_hi:[0,1,1]
	v_xor_b32_e32 v57, 0x80000000, v25
	v_xor_b32_e32 v56, 0x80000000, v24
	s_waitcnt vmcnt(12)
	v_pk_fma_f32 v[94:95], v[2:3], v[50:51], v[68:69]
	v_xor_b32_e32 v51, 0x80000000, v77
	v_xor_b32_e32 v50, 0x80000000, v76
	v_or_b32_e32 v68, s0, v166
	v_pk_fma_f32 v[52:53], v[72:73], v[52:53], v[56:57] op_sel_hi:[0,1,1]
	v_pk_fma_f32 v[96:97], v[72:73], v[54:55], v[50:51] op_sel_hi:[0,1,1]
	v_add_u32_e32 v50, -1, v68
	v_mad_u64_u32 v[54:55], s[0:1], v68, s63, v[30:31]
	v_lshlrev_b32_e32 v84, 16, v58
	v_and_b32_e32 v85, 0xffff0000, v58
	v_lshlrev_b32_e32 v88, 16, v59
	v_and_b32_e32 v89, 0xffff0000, v59
	v_lshlrev_b32_e32 v23, 16, v60
	v_and_b32_e32 v87, 0xffff0000, v60
	v_lshlrev_b32_e32 v104, 16, v61
	v_and_b32_e32 v105, 0xffff0000, v61
	v_lshlrev_b32_e32 v90, 16, v62
	v_and_b32_e32 v91, 0xffff0000, v62
	v_pk_fma_f32 v[24:25], v[4:5], v[52:53], v[24:25]
	v_mad_u64_u32 v[70:71], s[0:1], v50, s63, v[30:31]
	global_load_dwordx2 v[58:59], v[64:65], off
	global_load_dword v62, v[66:67], off
	global_load_dwordx2 v[50:51], v[54:55], off
	global_load_dwordx2 v[52:53], v[54:55], off offset:1024
	s_nop 0
	global_load_dwordx2 v[54:55], v[54:55], off offset:2048
	s_nop 0
	global_load_dwordx2 v[56:57], v[70:71], off
	global_load_dwordx2 v[60:61], v[70:71], off offset:1024
	global_load_dwordx2 v[64:65], v[70:71], off offset:2048
	v_mov_b32_e32 v69, v29
	v_lshlrev_b64 v[66:67], 10, v[68:69]
	v_lshl_add_u64 v[70:71], v[32:33], 0, v[66:67]
	v_lshl_add_u64 v[100:101], v[34:35], 0, v[66:67]
	v_lshlrev_b64 v[66:67], 5, v[68:69]
	v_lshl_add_u64 v[102:103], s[36:37], 0, v[66:67]
	global_load_dwordx2 v[66:67], v[70:71], off
	global_load_dwordx2 v[68:69], v[100:101], off
	s_nop 0
	global_load_dword v70, v[102:103], off
	v_xor_b32_e32 v99, 0x80000000, v75
	v_xor_b32_e32 v98, 0x80000000, v74
	v_pk_fma_f32 v[82:83], v[72:73], v[82:83], v[98:99] op_sel_hi:[0,1,1]
	v_mul_f32_e32 v23, 0xbfb8aa3b, v23
	s_waitcnt vmcnt(22)
	v_pk_fma_f32 v[98:99], v[6:7], v[82:83], v[74:75]
	v_exp_f32_e32 v82, v23
	v_mul_f32_e32 v23, 0xbfb8aa3b, v87
	v_xor_b32_e32 v75, 0x80000000, v79
	v_xor_b32_e32 v74, 0x80000000, v78
	v_exp_f32_e32 v83, v23
	v_mul_f32_e32 v23, 0xbfb8aa3b, v104
	v_pk_fma_f32 v[96:97], v[8:9], v[96:97], v[76:77]
	v_pk_fma_f32 v[74:75], v[72:73], v[84:85], v[74:75] op_sel_hi:[0,1,1]
	v_xor_b32_e32 v77, 0x80000000, v81
	v_xor_b32_e32 v76, 0x80000000, v80
	v_exp_f32_e32 v84, v23
	v_mul_f32_e32 v23, 0xbfb8aa3b, v105
	v_lshlrev_b32_e32 v92, 16, v63
	v_and_b32_e32 v93, 0xffff0000, v63
	v_pk_fma_f32 v[72:73], v[72:73], v[88:89], v[76:77] op_sel_hi:[0,1,1]
	v_exp_f32_e32 v85, v23
	s_movk_i32 s0, 0x500
	s_waitcnt vmcnt(19)
	v_pk_fma_f32 v[76:77], v[20:21], v[72:73], v[80:81]
	v_pk_add_f32 v[72:73], v[92:93], -1.0 op_sel_hi:[1,0]
	v_mul_lo_u32 v23, v28, s0
	v_pk_fma_f32 v[72:73], v[16:17], v[72:73], 1.0 op_sel_hi:[1,1,0]
	v_add_u32_e32 v23, 0, v23
	v_pk_mul_f32 v[80:81], v[96:97], v[72:73]
	v_lshl_add_u32 v73, v169, 4, v23
	ds_write_b128 v73, v[82:85]
	v_pk_mul_f32 v[82:83], v[12:13], v[96:97] neg_lo:[0,1] neg_hi:[0,1]
	v_pk_fma_f32 v[74:75], v[18:19], v[74:75], v[78:79]
	s_waitcnt vmcnt(14)
	v_pk_mul_f32 v[84:85], v[86:87], v[82:83] op_sel_hi:[0,1]
	v_pk_mul_f32 v[82:83], v[10:11], v[98:99] neg_lo:[0,1] neg_hi:[0,1]
	v_pk_add_f32 v[78:79], v[90:91], -1.0 op_sel_hi:[1,0]
	v_pk_mul_f32 v[82:83], v[86:87], v[82:83] op_sel_hi:[0,1]
	v_pk_fma_f32 v[78:79], v[14:15], v[78:79], 1.0 op_sel_hi:[1,1,0]
	ds_write_b128 v73, v[82:85] offset:256
	v_pk_mul_f32 v[84:85], v[84:85], v[92:93] neg_lo:[1,0] neg_hi:[1,0]
	v_pk_mul_f32 v[82:83], v[82:83], v[90:91] neg_lo:[1,0] neg_hi:[1,0]
	s_movk_i32 s0, 0xfb80
	v_pk_mul_f32 v[78:79], v[98:99], v[78:79]
	ds_write_b128 v73, v[82:85] offset:512
	ds_write_b128 v73, v[78:81] offset:768
	ds_write_b128 v73, v[74:77] offset:1024
	v_cvt_pk_bf16_f32 v77, v24, v25
	v_mul_lo_u32 v24, v28, s0
	v_cvt_pk_bf16_f32 v76, v94, v95
	v_add3_u32 v75, v23, v24, v22
	v_and_b32_e32 v22, 48, v0
	s_add_i32 s0, 0, 0x14000
	ds_write_b64 v75, v[76:77] offset:40960
	v_add_u32_e32 v76, s0, v22
	v_add_u32_e32 v63, 0, v22
	v_lshl_or_b32 v22, s62, 4, v169
	v_mul_lo_u32 v79, v22, s6
	v_lshl_or_b32 v22, s69, 4, v169
	v_mul_lo_u32 v74, v22, s6
	v_lshl_or_b32 v22, s70, 4, v169
	v_mul_lo_u32 v72, v22, s6
	v_lshl_or_b32 v22, s71, 4, v169
	v_cmp_eq_u32_e64 s[0:1], 0, v169
	v_add_u32_e32 v77, 48, v28
	v_or_b32_e32 v78, 64, v166
	v_mul_lo_u32 v71, v22, s6
	v_sub_u32_e32 v80, 0, v28
	v_add_u32_e32 v112, 4, v169
	v_and_b32_e32 v112, 8, v112
	v_lshlrev_b32_e32 v112, 1, v112
	v_xor_b32_e32 v113, v112, v76
	v_xor_b32_e32 v112, v112, v63
	v_add_u32_e32 v212, v113, v79
	v_add_u32_e32 v216, v112, v79
	v_add_u32_e32 v220, s68, v63
	v_add_u32_e32 v213, v113, v74
	v_add_u32_e32 v217, v112, v74
	v_add_u32_e32 v221, s66, v63
	v_add_u32_e32 v214, v113, v72
	v_add_u32_e32 v218, v112, v72
	v_add_u32_e32 v222, s65, v63
	v_add_u32_e32 v215, v113, v71
	v_add_u32_e32 v219, v112, v71
	v_add_u32_e32 v223, s64, v63
	s_waitcnt lgkmcnt(0)
	s_barrier
	s_branch .LBB0_1053
	s_nop 0
	s_nop 0
	s_nop 0
	s_nop 0

.LBB0_1103:
	s_add_u32 s40, s28, 0x6a00000
	s_addc_u32 s41, s29, 0
	s_add_u32 s46, s28, 0x7f00000
	s_addc_u32 s47, s29, 0
	s_add_u32 s36, s28, 0x8a00000
	s_addc_u32 s37, s29, 0
	v_readlane_b32 s0, v255, 3
	s_add_u32 s56, s28, 0xfd20000
	v_readlane_b32 s1, v255, 4
	s_addc_u32 s57, s29, 0
	s_andn2_b64 vcc, exec, s[0:1]
	s_cbranch_vccnz .LBB0_1531
	v_readlane_b32 s0, v255, 25
	v_mov_b32_e32 v3, 0
	v_readlane_b32 s1, v255, 26
	v_readlane_b32 s31, v255, 0
	s_bfe_u32 s10, s31, 0x20006
	v_lshl_add_u32 v149, v178, 2, 0
	v_or_b32_e32 v5, 0x200, v0
	s_lshl_b32 s64, s10, 5
	global_load_dword v174, v3, s[0:1]
	s_lshr_b32 s0, s31, 8
	s_lshl_b32 s65, s0, 7
	v_readlane_b32 s52, v255, 38
	v_lshlrev_b32_e32 v2, 4, v169
	v_lshlrev_b32_e32 v6, 4, v133
	s_movk_i32 s11, 0x110
	s_movk_i32 s30, 0x88
	v_lshrrev_b32_e32 v213, 4, v5
	v_lshl_add_u32 v216, s10, 14, v149
	v_readlane_b32 s53, v255, 39
	s_add_u32 s10, s52, s65
	v_lshrrev_b32_e32 v4, 5, v178
	v_mad_u32_u24 v212, v172, s11, v2
	v_mad_u32_u24 v215, v168, s30, v6
	v_lshl_add_u64 v[180:181], s[84:85], 0, v[2:3]
	v_mad_u32_u24 v217, v213, s11, v2
	v_lshlrev_b32_e32 v2, 1, v132
	s_addc_u32 s11, s53, 0
	v_lshlrev_b32_e32 v163, 3, v4
	v_lshlrev_b32_e32 v176, 4, v4
	v_lshlrev_b32_e32 v178, 2, v4
	v_lshrrev_b32_e32 v214, 3, v5
	v_add_u32_e32 v4, 0, v215
	v_lshl_add_u64 v[184:185], s[8:9], 0, v[2:3]
	v_lshlrev_b32_e32 v2, 4, v167
	s_cmp_eq_u32 s0, 1
	v_mov_b32_e32 v177, v3
	v_mov_b32_e32 v5, v3
	v_mad_u32_u24 v218, v214, s30, v6
	v_readlane_b32 s68, v255, 7
	v_add_u32_e32 v167, 0x4400, v4
	v_lshl_or_b32 v4, v172, 8, v2
	s_cselect_b64 s[8:9], -1, 0
	s_cmpk_lt_u32 s31, 0x100
	v_and_b32_e32 v147, 31, v0
	s_mov_b64 s[6:7], 0x9fa4000
	v_readlane_b32 s80, v255, 19
	v_readlane_b32 s81, v255, 20
	v_add_u32_e32 v8, 0, v218
	v_lshl_add_u64 v[186:187], s[10:11], 0, v[176:177]
	v_lshl_add_u64 v[6:7], s[28:29], 0, v[2:3]
	v_lshl_add_u64 v[4:5], s[28:29], 0, v[4:5]
	s_cselect_b64 s[58:59], -1, 0
	s_and_b32 s0, s31, 0xc0
	s_lshl_b32 s10, s31, 8
	s_add_i32 s66, 0, 0x23000
	v_readlane_b32 s52, v255, 23
	s_mov_b32 s1, 0
	s_movk_i32 s35, 0x1ff
	s_movk_i32 s62, 0x4080
	s_mov_b64 s[4:5], 0x4000
	v_mov_b32_e32 v151, 0x358637bd
	s_mov_b32 s63, 0x800000
	v_mov_b32_e32 v153, 0x150
	v_mov_b32_e32 v159, 0x204000
	v_mov_b32_e32 v161, 0xf149f2ca
	v_mul_u32_u24_e32 v165, 0x110, v147
	v_mul_u32_u24_e32 v171, 0x88, v147
	v_lshl_add_u64 v[182:183], s[80:81], 0, v[176:177]
	v_or_b32_e32 v219, s64, v147
	v_add_u32_e32 v220, 0, v212
	v_add_u32_e32 v221, 0, v217
	v_add_u32_e32 v177, 0x4400, v8
	v_lshl_add_u64 v[188:189], v[6:7], 0, s[6:7]
	v_lshl_add_u64 v[190:191], v[4:5], 0, s[6:7]
	v_lshl_add_u32 v222, s0, 8, v149
	s_or_b32 s67, s10, 0x3f00
	v_mov_b32_e32 v223, s66
	v_mbcnt_hi_u32_b32 v157, -1, v211
	v_readlane_b32 s53, v255, 24
	v_readlane_b32 s69, v255, 8
	v_readlane_b32 s70, v255, 9
	v_readlane_b32 s71, v255, 10
	v_readlane_b32 s72, v255, 11
	v_readlane_b32 s73, v255, 12
	v_readlane_b32 s74, v255, 13
	v_readlane_b32 s75, v255, 14
	v_readlane_b32 s76, v255, 15
	v_readlane_b32 s77, v255, 16
	s_waitcnt vmcnt(0)
	v_mov_b32_e32 v175, v174
	v_readlane_b32 s78, v255, 17
	v_readlane_b32 s79, v255, 18
	v_readlane_b32 s82, v255, 21
	v_readlane_b32 s83, v255, 22
	s_branch .LBB0_1107
	s_nop 0
	s_nop 0
	s_nop 0

.LBB0_1311:
	global_load_dword v3, v2, s[4:5] sc1
	s_mov_b64 s[6:7], -1
	s_waitcnt vmcnt(0)
	v_cmp_lt_u32_e32 vcc, 63, v3
	s_cbranch_vccnz .LBB0_1310
	s_sleep 4
	global_load_dword v3, v2, s[4:5] sc1
	s_waitcnt vmcnt(0)
	v_cmp_gt_u32_e32 vcc, 64, v3
	s_cbranch_vccz .LBB0_1310
	s_sleep 4
	global_load_dword v3, v2, s[4:5] sc1
	s_waitcnt vmcnt(0)
	v_cmp_gt_u32_e32 vcc, 64, v3
	s_cbranch_vccz .LBB0_1310
	s_sleep 4
	global_load_dword v3, v2, s[4:5] sc1
	s_waitcnt vmcnt(0)
	v_cmp_gt_u32_e32 vcc, 64, v3
	s_cbranch_vccz .LBB0_1310
	s_sleep 4
	global_load_dword v3, v2, s[4:5] sc1
	s_waitcnt vmcnt(0)
	v_cmp_gt_u32_e32 vcc, 64, v3
	s_cbranch_vccz .LBB0_1310
	s_add_i32 s8, s8, -5
	s_cmp_eq_u32 s8, 0
	s_cselect_b64 s[6:7], -1, 0
	s_sleep 4
	s_branch .LBB0_1310
	s_nop 0
	s_nop 0
	s_nop 0
	s_nop 0
	s_nop 0
	s_nop 0
	s_nop 0
	s_nop 0
	s_nop 0
	s_nop 0
	s_nop 0
	s_nop 0
